# instruction selection (strategy 7): P9 epilogue +1.0 adds packed into v_pk_add_f32 where register pairs allow, on top of v23
# baseline (speedup 1.0000x reference)
; __device__ __forceinline__ u32x4 pack8(f32x4 v0, f32x4 v1) { u32x4 w; w.x = cvt_pk_bf16(v0[0], v0[1]); w.y = cvt_pk_bf16(v0[2], v0[3]); w.z = cvt_pk_bf16(v1[0], v1[1]); w.w = cvt_pk_bf16(v1[2], v1[3]); return w; }
;     __device__ __forceinline__ void operator()(EPI_ARGS) const {
;         const int col0 = u.pn * 128 + wc * 32 + 8 * fq;
; #pragma unroll
;         for (int ai = 0; ai < 2; ++ai)
; #pragma unroll
;             for (int m = 0; m < 4; ++m) { const int row = EPI_ROW(ai, m); const float rs = __builtin_amdgcn_rsqf(rsq[row] * (1.f / DM) + RMS_EPS); f32x4 v0, v1;
;                 const float c1 = -1.4426950408889634f * rs, rs2 = rs * rs;
;                 { const f32x4 g = acc[ai][0][m][0], u = acc[ai][1][m][0]; f32x4 t = g * c1, r;
; #pragma unroll
;                   for (int e = 0; e < 4; ++e) t[e] = __builtin_amdgcn_exp2f(t[e]);
;                   t = t + 1.f;
; #pragma unroll
;                   for (int e = 0; e < 4; ++e) r[e] = __builtin_amdgcn_rcpf(t[e]);
;                   v0 = (g * u) * (r * rs2); }
;                 { const f32x4 g = acc[ai][0][m][1], u = acc[ai][1][m][1]; f32x4 t = g * c1, r;
; #pragma unroll
;                   for (int e = 0; e < 4; ++e) t[e] = __builtin_amdgcn_exp2f(t[e]);
;                   t = t + 1.f;
; #pragma unroll
;                   for (int e = 0; e < 4; ++e) r[e] = __builtin_amdgcn_rcpf(t[e]);
;                   v1 = (g * u) * (r * rs2); }
;                 *(u32x4*)(H + (size_t)row * DFF + col0) = pack8(v0, v1);
;                 if (m & 1) asm volatile("" ::: "memory"); }
.LBB0_899:
	v_lshl_add_u32 v132, s50, 8, v139
	v_ashrrev_i32_e32 v133, 31, v132
	v_lshl_add_u64 v[154:155], v[132:133], 2, s[8:9]
	global_load_dword v224, v[154:155], off
	global_load_dword v225, v[154:155], off offset:64
	global_load_dword v226, v[154:155], off offset:128
	global_load_dword v227, v[154:155], off offset:192
	global_load_dword v228, v[154:155], off offset:512
	global_load_dword v229, v[154:155], off offset:576
	global_load_dword v230, v[154:155], off offset:640
	global_load_dword v231, v[154:155], off offset:704
	v_pk_mul_f32 v[126:127], v[118:119], v[126:127]
	v_pk_mul_f32 v[124:125], v[116:117], v[124:125]
	v_pk_mul_f32 v[156:157], v[114:115], v[122:123]
	v_pk_mul_f32 v[158:159], v[112:113], v[120:121]
	v_lshl_or_b32 v154, s49, 7, v146
	v_mov_b64_e32 v[120:121], s[64:65]
	v_ashrrev_i32_e32 v155, 31, v154
	v_mad_i64_i32 v[166:167], s[26:27], v132, s46, v[120:121]
	v_or_b32_e32 v172, 16, v132
	v_lshlrev_b64 v[122:123], 1, v[154:155]
	v_ashrrev_i32_e32 v173, 31, v172
	v_lshl_add_u64 v[154:155], v[166:167], 0, v[122:123]
	v_lshl_add_u64 v[166:167], v[172:173], 2, s[8:9]
	v_pk_mul_f32 v[110:111], v[102:103], v[110:111]
	v_pk_mul_f32 v[108:109], v[100:101], v[108:109]
	v_pk_mul_f32 v[106:107], v[98:99], v[106:107]
	v_pk_mul_f32 v[104:105], v[96:97], v[104:105]
	v_pk_mul_f32 v[94:95], v[86:87], v[94:95]
	v_pk_mul_f32 v[92:93], v[84:85], v[92:93]
	v_pk_mul_f32 v[90:91], v[82:83], v[90:91]
	v_pk_mul_f32 v[88:89], v[80:81], v[88:89]
	v_pk_mul_f32 v[78:79], v[70:71], v[78:79]
	v_pk_mul_f32 v[76:77], v[68:69], v[76:77]
	v_pk_mul_f32 v[74:75], v[66:67], v[74:75]
	v_pk_mul_f32 v[72:73], v[64:65], v[72:73]
	v_pk_mul_f32 v[62:63], v[54:55], v[62:63]
	v_pk_mul_f32 v[60:61], v[52:53], v[60:61]
	v_pk_mul_f32 v[58:59], v[50:51], v[58:59]
	v_pk_mul_f32 v[56:57], v[48:49], v[56:57]
	v_pk_mul_f32 v[46:47], v[38:39], v[46:47]
	v_pk_mul_f32 v[44:45], v[36:37], v[44:45]
	v_pk_mul_f32 v[42:43], v[34:35], v[42:43]
	v_pk_mul_f32 v[40:41], v[32:33], v[40:41]
	v_pk_mul_f32 v[30:31], v[22:23], v[30:31]
	v_pk_mul_f32 v[28:29], v[20:21], v[28:29]
	v_pk_mul_f32 v[26:27], v[18:19], v[26:27]
	v_pk_mul_f32 v[24:25], v[16:17], v[24:25]
	v_pk_mul_f32 v[14:15], v[10:11], v[14:15]
	v_pk_mul_f32 v[12:13], v[8:9], v[12:13]
	v_pk_mul_f32 v[2:3], v[6:7], v[2:3]
	v_pk_mul_f32 v[0:1], v[4:5], v[0:1]
	s_andn2_b64 vcc, exec, s[4:5]
	s_mov_b64 s[4:5], -1
	s_waitcnt vmcnt(7)
	v_fmamk_f32 v133, v224, 0x3a000000, v152
	v_rsq_f32_e32 v133, v133
	s_nop 0
	v_mul_f32_e32 v174, 0xbfb8aa3b, v133
	v_pk_mul_f32 v[118:119], v[118:119], v[174:175] op_sel_hi:[1,0]
	v_pk_mul_f32 v[116:117], v[116:117], v[174:175] op_sel_hi:[1,0]
	v_pk_mul_f32 v[114:115], v[114:115], v[174:175] op_sel_hi:[1,0]
	v_pk_mul_f32 v[112:113], v[112:113], v[174:175] op_sel_hi:[1,0]
	v_exp_f32_e32 v116, v116
	v_exp_f32_e32 v117, v117
	v_exp_f32_e32 v118, v118
	v_exp_f32_e32 v119, v119
	v_exp_f32_e32 v112, v112
	v_exp_f32_e32 v113, v113
	v_exp_f32_e32 v114, v114
	v_exp_f32_e32 v115, v115
	v_pk_add_f32 v[116:117], v[116:117], 1.0 op_sel_hi:[1,0]
	v_pk_add_f32 v[118:119], v[118:119], 1.0 op_sel_hi:[1,0]
	v_mul_f32_e32 v176, v133, v133
	v_add_f32_e32 v133, 1.0, v112
	v_add_f32_e32 v153, 1.0, v113
	v_add_f32_e32 v161, 1.0, v114
	v_add_f32_e32 v163, 1.0, v115
	v_rcp_f32_e32 v112, v116
	v_rcp_f32_e32 v113, v117
	v_rcp_f32_e32 v114, v118
	v_rcp_f32_e32 v115, v119
	v_rcp_f32_e32 v116, v133
	v_rcp_f32_e32 v117, v153
	v_rcp_f32_e32 v118, v161
	v_rcp_f32_e32 v119, v163
	v_pk_mul_f32 v[112:113], v[176:177], v[112:113] op_sel_hi:[0,1]
	v_pk_mul_f32 v[114:115], v[176:177], v[114:115] op_sel_hi:[0,1]
	v_pk_mul_f32 v[116:117], v[176:177], v[116:117] op_sel_hi:[0,1]
	v_pk_mul_f32 v[118:119], v[176:177], v[118:119] op_sel_hi:[0,1]
	v_pk_mul_f32 v[114:115], v[126:127], v[114:115]
	v_pk_mul_f32 v[112:113], v[124:125], v[112:113]
	v_pk_mul_f32 v[118:119], v[156:157], v[118:119]
	v_pk_mul_f32 v[116:117], v[158:159], v[116:117]
	v_cvt_pk_bf16_f32 v112, v112, v113
	v_cvt_pk_bf16_f32 v113, v114, v115
	s_nop 0
	v_cvt_pk_bf16_f32 v114, v116, v117
	v_cvt_pk_bf16_f32 v115, v118, v119
	global_store_dwordx4 v[154:155], v[112:115], off
	s_nop 1
	s_nop 0
	v_or_b32_e32 v112, 32, v132
	v_mad_i64_i32 v[114:115], s[26:27], v172, s46, v[120:121]
	v_lshl_add_u64 v[114:115], v[114:115], 0, v[122:123]
	s_waitcnt vmcnt(7)
	v_fmamk_f32 v113, v225, 0x3a000000, v152
	v_rsq_f32_e32 v119, v113
	v_ashrrev_i32_e32 v113, 31, v112
	v_lshl_add_u64 v[116:117], v[112:113], 2, s[8:9]
	v_mul_f32_e32 v118, 0xbfb8aa3b, v119
	v_pk_mul_f32 v[102:103], v[102:103], v[118:119] op_sel_hi:[1,0]
	v_pk_mul_f32 v[100:101], v[100:101], v[118:119] op_sel_hi:[1,0]
	v_pk_mul_f32 v[98:99], v[98:99], v[118:119] op_sel_hi:[1,0]
	v_pk_mul_f32 v[96:97], v[96:97], v[118:119] op_sel_hi:[1,0]
	v_exp_f32_e32 v100, v100
	v_exp_f32_e32 v101, v101
	v_exp_f32_e32 v102, v102
	v_exp_f32_e32 v103, v103
	v_exp_f32_e32 v96, v96
	v_exp_f32_e32 v97, v97
	v_exp_f32_e32 v98, v98
	v_exp_f32_e32 v99, v99
	v_pk_add_f32 v[100:101], v[100:101], 1.0 op_sel_hi:[1,0]
	v_pk_add_f32 v[102:103], v[102:103], 1.0 op_sel_hi:[1,0]
	v_mul_f32_e32 v124, v119, v119
	v_add_f32_e32 v113, 1.0, v96
	v_add_f32_e32 v118, 1.0, v97
	v_add_f32_e32 v119, 1.0, v98
	v_add_f32_e32 v125, 1.0, v99
	v_rcp_f32_e32 v96, v100
	v_rcp_f32_e32 v97, v101
	v_rcp_f32_e32 v98, v102
	v_rcp_f32_e32 v99, v103
	v_rcp_f32_e32 v100, v113
	v_rcp_f32_e32 v101, v118
	v_rcp_f32_e32 v102, v119
	v_rcp_f32_e32 v103, v125
	v_pk_mul_f32 v[96:97], v[124:125], v[96:97] op_sel_hi:[0,1]
	v_pk_mul_f32 v[98:99], v[124:125], v[98:99] op_sel_hi:[0,1]
	v_pk_mul_f32 v[100:101], v[124:125], v[100:101] op_sel_hi:[0,1]
	v_pk_mul_f32 v[102:103], v[124:125], v[102:103] op_sel_hi:[0,1]
	v_pk_mul_f32 v[98:99], v[110:111], v[98:99]
	v_pk_mul_f32 v[96:97], v[108:109], v[96:97]
	v_pk_mul_f32 v[102:103], v[106:107], v[102:103]
	v_pk_mul_f32 v[100:101], v[104:105], v[100:101]
	v_cvt_pk_bf16_f32 v96, v96, v97
	v_cvt_pk_bf16_f32 v97, v98, v99
	s_nop 0
	v_cvt_pk_bf16_f32 v98, v100, v101
	v_cvt_pk_bf16_f32 v99, v102, v103
	global_store_dwordx4 v[114:115], v[96:99], off
	s_nop 1
	s_nop 0
	v_or_b32_e32 v96, 48, v132
	v_mad_i64_i32 v[98:99], s[26:27], v112, s46, v[120:121]
	v_lshl_add_u64 v[98:99], v[98:99], 0, v[122:123]
	s_waitcnt vmcnt(7)
; __device__ __forceinline__ u32x4 pack8(f32x4 v0, f32x4 v1) { u32x4 w; w.x = cvt_pk_bf16(v0[0], v0[1]); w.y = cvt_pk_bf16(v0[2], v0[3]); w.z = cvt_pk_bf16(v1[0], v1[1]); w.w = cvt_pk_bf16(v1[2], v1[3]); return w; }
;     __device__ __forceinline__ void operator()(EPI_ARGS) const {
;     ...
;             for (int m = 0; m < 4; ++m) { const int row = EPI_ROW(ai, m); const float rs = __builtin_amdgcn_rsqf(rsq[row] * (1.f / DM) + RMS_EPS); f32x4 v0, v1;
;                 const float c1 = -1.4426950408889634f * rs, rs2 = rs * rs;
;                 { const f32x4 g = acc[ai][0][m][0], u = acc[ai][1][m][0]; f32x4 t = g * c1, r;
; #pragma unroll
;                   for (int e = 0; e < 4; ++e) t[e] = __builtin_amdgcn_exp2f(t[e]);
;                   t = t + 1.f;
; #pragma unroll
;                   for (int e = 0; e < 4; ++e) r[e] = __builtin_amdgcn_rcpf(t[e]);
;                   v0 = (g * u) * (r * rs2); }
;                 { const f32x4 g = acc[ai][0][m][1], u = acc[ai][1][m][1]; f32x4 t = g * c1, r;
; #pragma unroll
;                   for (int e = 0; e < 4; ++e) t[e] = __builtin_amdgcn_exp2f(t[e]);
;                   t = t + 1.f;
; #pragma unroll
;                   for (int e = 0; e < 4; ++e) r[e] = __builtin_amdgcn_rcpf(t[e]);
;                   v1 = (g * u) * (r * rs2); }
;                 *(u32x4*)(H + (size_t)row * DFF + col0) = pack8(v0, v1);
;                 if (m & 1) asm volatile("" ::: "memory"); }
	v_fmamk_f32 v97, v226, 0x3a000000, v152
	v_rsq_f32_e32 v103, v97
	v_ashrrev_i32_e32 v97, 31, v96
	v_lshl_add_u64 v[100:101], v[96:97], 2, s[8:9]
	v_mul_f32_e32 v102, 0xbfb8aa3b, v103
	v_pk_mul_f32 v[86:87], v[86:87], v[102:103] op_sel_hi:[1,0]
	v_pk_mul_f32 v[84:85], v[84:85], v[102:103] op_sel_hi:[1,0]
	v_pk_mul_f32 v[82:83], v[82:83], v[102:103] op_sel_hi:[1,0]
	v_pk_mul_f32 v[80:81], v[80:81], v[102:103] op_sel_hi:[1,0]
	v_exp_f32_e32 v84, v84
	v_exp_f32_e32 v85, v85
	v_exp_f32_e32 v86, v86
	v_exp_f32_e32 v87, v87
	v_exp_f32_e32 v80, v80
	v_exp_f32_e32 v81, v81
	v_exp_f32_e32 v82, v82
	v_exp_f32_e32 v83, v83
	v_pk_add_f32 v[84:85], v[84:85], 1.0 op_sel_hi:[1,0]
	v_pk_add_f32 v[86:87], v[86:87], 1.0 op_sel_hi:[1,0]
	v_mul_f32_e32 v104, v103, v103
	v_add_f32_e32 v97, 1.0, v80
	v_add_f32_e32 v102, 1.0, v81
	v_add_f32_e32 v103, 1.0, v82
	v_add_f32_e32 v105, 1.0, v83
	v_rcp_f32_e32 v80, v84
	v_rcp_f32_e32 v81, v85
	v_rcp_f32_e32 v82, v86
	v_rcp_f32_e32 v83, v87
	v_rcp_f32_e32 v84, v97
	v_rcp_f32_e32 v85, v102
	v_rcp_f32_e32 v86, v103
	v_rcp_f32_e32 v87, v105
	v_pk_mul_f32 v[80:81], v[104:105], v[80:81] op_sel_hi:[0,1]
	v_pk_mul_f32 v[82:83], v[104:105], v[82:83] op_sel_hi:[0,1]
	v_pk_mul_f32 v[84:85], v[104:105], v[84:85] op_sel_hi:[0,1]
	v_pk_mul_f32 v[86:87], v[104:105], v[86:87] op_sel_hi:[0,1]
	v_pk_mul_f32 v[82:83], v[94:95], v[82:83]
	v_pk_mul_f32 v[80:81], v[92:93], v[80:81]
	v_pk_mul_f32 v[86:87], v[90:91], v[86:87]
	v_pk_mul_f32 v[84:85], v[88:89], v[84:85]
	v_cvt_pk_bf16_f32 v80, v80, v81
	v_cvt_pk_bf16_f32 v81, v82, v83
	s_nop 0
	v_cvt_pk_bf16_f32 v82, v84, v85
	v_cvt_pk_bf16_f32 v83, v86, v87
	global_store_dwordx4 v[98:99], v[80:83], off
	s_nop 1
	s_nop 0
	v_add_u32_e32 v80, 0x80, v132
	v_mad_i64_i32 v[82:83], s[26:27], v96, s46, v[120:121]
	v_lshl_add_u64 v[82:83], v[82:83], 0, v[122:123]
	s_waitcnt vmcnt(7)
	v_fmamk_f32 v81, v227, 0x3a000000, v152
	v_rsq_f32_e32 v87, v81
	v_ashrrev_i32_e32 v81, 31, v80
	v_lshl_add_u64 v[84:85], v[80:81], 2, s[8:9]
	v_mul_f32_e32 v86, 0xbfb8aa3b, v87
	v_pk_mul_f32 v[70:71], v[70:71], v[86:87] op_sel_hi:[1,0]
	v_pk_mul_f32 v[68:69], v[68:69], v[86:87] op_sel_hi:[1,0]
	v_pk_mul_f32 v[66:67], v[66:67], v[86:87] op_sel_hi:[1,0]
	v_pk_mul_f32 v[64:65], v[64:65], v[86:87] op_sel_hi:[1,0]
	v_exp_f32_e32 v68, v68
	v_exp_f32_e32 v69, v69
	v_exp_f32_e32 v70, v70
	v_exp_f32_e32 v71, v71
	v_exp_f32_e32 v64, v64
	v_exp_f32_e32 v65, v65
	v_exp_f32_e32 v66, v66
	v_exp_f32_e32 v67, v67
	v_pk_add_f32 v[68:69], v[68:69], 1.0 op_sel_hi:[1,0]
	v_pk_add_f32 v[70:71], v[70:71], 1.0 op_sel_hi:[1,0]
	v_mul_f32_e32 v88, v87, v87
	v_add_f32_e32 v81, 1.0, v64
	v_add_f32_e32 v86, 1.0, v65
	v_add_f32_e32 v87, 1.0, v66
	v_add_f32_e32 v89, 1.0, v67
	v_rcp_f32_e32 v64, v68
	v_rcp_f32_e32 v65, v69
	v_rcp_f32_e32 v66, v70
	v_rcp_f32_e32 v67, v71
	v_rcp_f32_e32 v68, v81
	v_rcp_f32_e32 v69, v86
	v_rcp_f32_e32 v70, v87
	v_rcp_f32_e32 v71, v89
	v_pk_mul_f32 v[64:65], v[88:89], v[64:65] op_sel_hi:[0,1]
	v_pk_mul_f32 v[66:67], v[88:89], v[66:67] op_sel_hi:[0,1]
	v_pk_mul_f32 v[68:69], v[88:89], v[68:69] op_sel_hi:[0,1]
	v_pk_mul_f32 v[70:71], v[88:89], v[70:71] op_sel_hi:[0,1]
	v_pk_mul_f32 v[66:67], v[78:79], v[66:67]
	v_pk_mul_f32 v[64:65], v[76:77], v[64:65]
	v_pk_mul_f32 v[70:71], v[74:75], v[70:71]
	v_pk_mul_f32 v[68:69], v[72:73], v[68:69]
	v_cvt_pk_bf16_f32 v64, v64, v65
	v_cvt_pk_bf16_f32 v65, v66, v67
	s_nop 0
	v_cvt_pk_bf16_f32 v66, v68, v69
	v_cvt_pk_bf16_f32 v67, v70, v71
	global_store_dwordx4 v[82:83], v[64:67], off
	s_nop 1
	s_nop 0
	v_add_u32_e32 v64, 0x90, v132
	v_mad_i64_i32 v[66:67], s[26:27], v80, s46, v[120:121]
	v_lshl_add_u64 v[66:67], v[66:67], 0, v[122:123]
	s_waitcnt vmcnt(7)
	v_fmamk_f32 v65, v228, 0x3a000000, v152
	v_rsq_f32_e32 v71, v65
	v_ashrrev_i32_e32 v65, 31, v64
	v_lshl_add_u64 v[68:69], v[64:65], 2, s[8:9]
	v_mul_f32_e32 v70, 0xbfb8aa3b, v71
	v_pk_mul_f32 v[54:55], v[54:55], v[70:71] op_sel_hi:[1,0]
	v_pk_mul_f32 v[52:53], v[52:53], v[70:71] op_sel_hi:[1,0]
	v_pk_mul_f32 v[50:51], v[50:51], v[70:71] op_sel_hi:[1,0]
	v_pk_mul_f32 v[48:49], v[48:49], v[70:71] op_sel_hi:[1,0]
	v_exp_f32_e32 v52, v52
	v_exp_f32_e32 v53, v53
	v_exp_f32_e32 v54, v54
	v_exp_f32_e32 v55, v55
	v_exp_f32_e32 v48, v48
	v_exp_f32_e32 v49, v49
	v_exp_f32_e32 v50, v50
	v_exp_f32_e32 v51, v51
	v_pk_add_f32 v[52:53], v[52:53], 1.0 op_sel_hi:[1,0]
	v_pk_add_f32 v[54:55], v[54:55], 1.0 op_sel_hi:[1,0]
	v_mul_f32_e32 v72, v71, v71
	v_add_f32_e32 v65, 1.0, v48
	v_add_f32_e32 v70, 1.0, v49
	v_add_f32_e32 v71, 1.0, v50
	v_add_f32_e32 v73, 1.0, v51
	v_rcp_f32_e32 v48, v52
	v_rcp_f32_e32 v49, v53
	v_rcp_f32_e32 v50, v54
	v_rcp_f32_e32 v51, v55
	v_rcp_f32_e32 v52, v65
	v_rcp_f32_e32 v53, v70
	v_rcp_f32_e32 v54, v71
	v_rcp_f32_e32 v55, v73
	v_pk_mul_f32 v[48:49], v[72:73], v[48:49] op_sel_hi:[0,1]
	v_pk_mul_f32 v[50:51], v[72:73], v[50:51] op_sel_hi:[0,1]
	v_pk_mul_f32 v[52:53], v[72:73], v[52:53] op_sel_hi:[0,1]
	v_pk_mul_f32 v[54:55], v[72:73], v[54:55] op_sel_hi:[0,1]
	v_pk_mul_f32 v[50:51], v[62:63], v[50:51]
	v_pk_mul_f32 v[48:49], v[60:61], v[48:49]
	v_pk_mul_f32 v[54:55], v[58:59], v[54:55]
	v_pk_mul_f32 v[52:53], v[56:57], v[52:53]
	v_cvt_pk_bf16_f32 v48, v48, v49
	v_cvt_pk_bf16_f32 v49, v50, v51
	s_nop 0
	v_cvt_pk_bf16_f32 v50, v52, v53
	v_cvt_pk_bf16_f32 v51, v54, v55
	global_store_dwordx4 v[66:67], v[48:51], off
	s_nop 1
	s_nop 0
	v_add_u32_e32 v48, 0xa0, v132
	v_mad_i64_i32 v[50:51], s[26:27], v64, s46, v[120:121]
	v_lshl_add_u64 v[50:51], v[50:51], 0, v[122:123]
	s_waitcnt vmcnt(7)
; __device__ __forceinline__ u32x4 pack8(f32x4 v0, f32x4 v1) { u32x4 w; w.x = cvt_pk_bf16(v0[0], v0[1]); w.y = cvt_pk_bf16(v0[2], v0[3]); w.z = cvt_pk_bf16(v1[0], v1[1]); w.w = cvt_pk_bf16(v1[2], v1[3]); return w; }
; #define PG8_BAR __builtin_amdgcn_s_barrier()
; template <class Epi, class Sched, bool ALIGN_EPI = true>
; __device__ __forceinline__ void gemm_phase(PG8_LAS unsigned char* lds, const Gemm g, const Sched& S, const Epi& E) {
;     ...
;         if (!has_next) break;
; #pragma unroll
;         for (int a = 0; a < 2; ++a)
; #pragma unroll
;             for (int b = 0; b < 2; ++b)
; #pragma unroll
;                 for (int m = 0; m < 4; ++m)
; #pragma unroll
;                     for (int n = 0; n < 2; ++n) acc[a][b][m][n] = (f32x4){0.f, 0.f, 0.f, 0.f};
;         cur = nxt; cA = nA; cB = nB; ++ui;
;         if constexpr (ALIGN_EPI) { if (wr == 1) PG8_BAR; }
;     __device__ __forceinline__ void operator()(EPI_ARGS) const {
;     ...
;             for (int m = 0; m < 4; ++m) { const int row = EPI_ROW(ai, m); const float rs = __builtin_amdgcn_rsqf(rsq[row] * (1.f / DM) + RMS_EPS); f32x4 v0, v1;
;                 const float c1 = -1.4426950408889634f * rs, rs2 = rs * rs;
;                 { const f32x4 g = acc[ai][0][m][0], u = acc[ai][1][m][0]; f32x4 t = g * c1, r;
; #pragma unroll
;                   for (int e = 0; e < 4; ++e) t[e] = __builtin_amdgcn_exp2f(t[e]);
;                   t = t + 1.f;
; #pragma unroll
;                   for (int e = 0; e < 4; ++e) r[e] = __builtin_amdgcn_rcpf(t[e]);
;                   v0 = (g * u) * (r * rs2); }
;                 { const f32x4 g = acc[ai][0][m][1], u = acc[ai][1][m][1]; f32x4 t = g * c1, r;
; #pragma unroll
;                   for (int e = 0; e < 4; ++e) t[e] = __builtin_amdgcn_exp2f(t[e]);
;                   t = t + 1.f;
; #pragma unroll
;                   for (int e = 0; e < 4; ++e) r[e] = __builtin_amdgcn_rcpf(t[e]);
;                   v1 = (g * u) * (r * rs2); }
;                 *(u32x4*)(H + (size_t)row * DFF + col0) = pack8(v0, v1);
;                 if (m & 1) asm volatile("" ::: "memory"); }
	v_fmamk_f32 v49, v229, 0x3a000000, v152
	v_rsq_f32_e32 v55, v49
	v_ashrrev_i32_e32 v49, 31, v48
	v_lshl_add_u64 v[52:53], v[48:49], 2, s[8:9]
	v_mul_f32_e32 v54, 0xbfb8aa3b, v55
	v_pk_mul_f32 v[38:39], v[38:39], v[54:55] op_sel_hi:[1,0]
	v_pk_mul_f32 v[36:37], v[36:37], v[54:55] op_sel_hi:[1,0]
	v_pk_mul_f32 v[34:35], v[34:35], v[54:55] op_sel_hi:[1,0]
	v_pk_mul_f32 v[32:33], v[32:33], v[54:55] op_sel_hi:[1,0]
	v_exp_f32_e32 v36, v36
	v_exp_f32_e32 v37, v37
	v_exp_f32_e32 v38, v38
	v_exp_f32_e32 v39, v39
	v_exp_f32_e32 v32, v32
	v_exp_f32_e32 v33, v33
	v_exp_f32_e32 v34, v34
	v_exp_f32_e32 v35, v35
	v_pk_add_f32 v[36:37], v[36:37], 1.0 op_sel_hi:[1,0]
	v_pk_add_f32 v[38:39], v[38:39], 1.0 op_sel_hi:[1,0]
	v_mul_f32_e32 v56, v55, v55
	v_add_f32_e32 v49, 1.0, v32
	v_add_f32_e32 v54, 1.0, v33
	v_add_f32_e32 v55, 1.0, v34
	v_add_f32_e32 v57, 1.0, v35
	v_rcp_f32_e32 v32, v36
	v_rcp_f32_e32 v33, v37
	v_rcp_f32_e32 v34, v38
	v_rcp_f32_e32 v35, v39
	v_rcp_f32_e32 v36, v49
	v_rcp_f32_e32 v37, v54
	v_rcp_f32_e32 v38, v55
	v_rcp_f32_e32 v39, v57
	v_pk_mul_f32 v[32:33], v[56:57], v[32:33] op_sel_hi:[0,1]
	v_pk_mul_f32 v[34:35], v[56:57], v[34:35] op_sel_hi:[0,1]
	v_pk_mul_f32 v[36:37], v[56:57], v[36:37] op_sel_hi:[0,1]
	v_pk_mul_f32 v[38:39], v[56:57], v[38:39] op_sel_hi:[0,1]
	v_pk_mul_f32 v[34:35], v[46:47], v[34:35]
	v_pk_mul_f32 v[32:33], v[44:45], v[32:33]
	v_pk_mul_f32 v[38:39], v[42:43], v[38:39]
	v_pk_mul_f32 v[36:37], v[40:41], v[36:37]
	v_cvt_pk_bf16_f32 v32, v32, v33
	v_cvt_pk_bf16_f32 v33, v34, v35
	s_nop 0
	v_cvt_pk_bf16_f32 v34, v36, v37
	v_cvt_pk_bf16_f32 v35, v38, v39
	global_store_dwordx4 v[50:51], v[32:35], off
	s_nop 1
	s_nop 0
	v_add_u32_e32 v32, 0xb0, v132
	v_mad_i64_i32 v[34:35], s[26:27], v48, s46, v[120:121]
	v_lshl_add_u64 v[34:35], v[34:35], 0, v[122:123]
	s_waitcnt vmcnt(7)
	v_fmamk_f32 v33, v230, 0x3a000000, v152
	v_rsq_f32_e32 v39, v33
	v_ashrrev_i32_e32 v33, 31, v32
	v_lshl_add_u64 v[36:37], v[32:33], 2, s[8:9]
	v_mul_f32_e32 v38, 0xbfb8aa3b, v39
	v_pk_mul_f32 v[22:23], v[22:23], v[38:39] op_sel_hi:[1,0]
	v_pk_mul_f32 v[20:21], v[20:21], v[38:39] op_sel_hi:[1,0]
	v_pk_mul_f32 v[18:19], v[18:19], v[38:39] op_sel_hi:[1,0]
	v_pk_mul_f32 v[16:17], v[16:17], v[38:39] op_sel_hi:[1,0]
	v_exp_f32_e32 v20, v20
	v_exp_f32_e32 v21, v21
	v_exp_f32_e32 v22, v22
	v_exp_f32_e32 v23, v23
	v_exp_f32_e32 v16, v16
	v_exp_f32_e32 v17, v17
	v_exp_f32_e32 v18, v18
	v_exp_f32_e32 v19, v19
	v_pk_add_f32 v[20:21], v[20:21], 1.0 op_sel_hi:[1,0]
	v_pk_add_f32 v[22:23], v[22:23], 1.0 op_sel_hi:[1,0]
	v_mul_f32_e32 v40, v39, v39
	v_add_f32_e32 v33, 1.0, v16
	v_add_f32_e32 v38, 1.0, v17
	v_add_f32_e32 v39, 1.0, v18
	v_add_f32_e32 v41, 1.0, v19
	v_rcp_f32_e32 v16, v20
	v_rcp_f32_e32 v17, v21
	v_rcp_f32_e32 v18, v22
	v_rcp_f32_e32 v19, v23
	v_rcp_f32_e32 v20, v33
	v_rcp_f32_e32 v21, v38
	v_rcp_f32_e32 v22, v39
	v_rcp_f32_e32 v23, v41
	v_pk_mul_f32 v[16:17], v[40:41], v[16:17] op_sel_hi:[0,1]
	v_pk_mul_f32 v[18:19], v[40:41], v[18:19] op_sel_hi:[0,1]
	v_pk_mul_f32 v[20:21], v[40:41], v[20:21] op_sel_hi:[0,1]
	v_pk_mul_f32 v[22:23], v[40:41], v[22:23] op_sel_hi:[0,1]
	v_pk_mul_f32 v[18:19], v[30:31], v[18:19]
	v_pk_mul_f32 v[16:17], v[28:29], v[16:17]
	v_pk_mul_f32 v[22:23], v[26:27], v[22:23]
	v_pk_mul_f32 v[20:21], v[24:25], v[20:21]
	v_cvt_pk_bf16_f32 v16, v16, v17
	v_cvt_pk_bf16_f32 v17, v18, v19
	s_nop 0
	v_cvt_pk_bf16_f32 v18, v20, v21
	v_cvt_pk_bf16_f32 v19, v22, v23
	global_store_dwordx4 v[34:35], v[16:19], off
	s_nop 1
	s_waitcnt vmcnt(7)
	v_fmamk_f32 v16, v231, 0x3a000000, v152
	v_rsq_f32_e32 v19, v16
	v_mad_i64_i32 v[16:17], s[26:27], v32, s46, v[120:121]
	v_lshl_add_u64 v[16:17], v[16:17], 0, v[122:123]
	v_mul_f32_e32 v18, 0xbfb8aa3b, v19
	v_pk_mul_f32 v[10:11], v[10:11], v[18:19] op_sel_hi:[1,0]
	v_pk_mul_f32 v[8:9], v[8:9], v[18:19] op_sel_hi:[1,0]
	v_pk_mul_f32 v[6:7], v[6:7], v[18:19] op_sel_hi:[1,0]
	v_pk_mul_f32 v[4:5], v[4:5], v[18:19] op_sel_hi:[1,0]
	v_exp_f32_e32 v8, v8
	v_exp_f32_e32 v9, v9
	v_exp_f32_e32 v10, v10
	v_exp_f32_e32 v11, v11
	v_exp_f32_e32 v4, v4
	v_exp_f32_e32 v5, v5
	v_exp_f32_e32 v6, v6
	v_exp_f32_e32 v7, v7
	v_mul_f32_e32 v20, v19, v19
	v_pk_add_f32 v[8:9], v[8:9], 1.0 op_sel_hi:[1,0]
	v_pk_add_f32 v[10:11], v[10:11], 1.0 op_sel_hi:[1,0]
	v_add_f32_e32 v18, 1.0, v4
	v_add_f32_e32 v19, 1.0, v5
	v_add_f32_e32 v21, 1.0, v6
	v_add_f32_e32 v22, 1.0, v7
	v_rcp_f32_e32 v4, v8
	v_rcp_f32_e32 v5, v9
	v_rcp_f32_e32 v6, v10
	v_rcp_f32_e32 v7, v11
	v_rcp_f32_e32 v8, v18
	v_rcp_f32_e32 v9, v19
	v_rcp_f32_e32 v10, v21
	v_rcp_f32_e32 v11, v22
	v_pk_mul_f32 v[4:5], v[20:21], v[4:5] op_sel_hi:[0,1]
	v_pk_mul_f32 v[8:9], v[20:21], v[8:9] op_sel_hi:[0,1]
	v_pk_mul_f32 v[6:7], v[20:21], v[6:7] op_sel_hi:[0,1]
	v_pk_mul_f32 v[10:11], v[20:21], v[10:11] op_sel_hi:[0,1]
	v_pk_mul_f32 v[10:11], v[2:3], v[10:11]
	v_pk_mul_f32 v[2:3], v[0:1], v[8:9]
	v_pk_mul_f32 v[6:7], v[14:15], v[6:7]
	v_pk_mul_f32 v[4:5], v[12:13], v[4:5]
	s_nop 0
	v_cvt_pk_bf16_f32 v0, v4, v5
	v_cvt_pk_bf16_f32 v1, v6, v7
	v_cvt_pk_bf16_f32 v2, v2, v3
	v_cvt_pk_bf16_f32 v3, v10, v11
	global_store_dwordx4 v[16:17], v[0:3], off
	s_cbranch_vccnz .LBB0_892
	s_andn2_b64 vcc, exec, s[6:7]
	s_cbranch_vccnz .LBB0_891
	s_barrier
	s_branch .LBB0_891
